# ROW1 row loop: next row's x and mix loads stay in flight during the current row (conversion + one counted wait moved to the top of the next trip; merge-point drains removed)
# speedup vs baseline: 1.0082x; 1.0029x over previous
; __device__ __forceinline__ f32x4 bf4(u32x2 q) { return (f32x4){__uint_as_float(q.x << 16), __uint_as_float(q.x & 0xffff0000u), __uint_as_float(q.y << 16), __uint_as_float(q.y & 0xffff0000u)}; }
; __device__ __forceinline__ void phase_row1(const Frame& F, int l) {
;     ...
;     for (int chunk = F.bid; chunk < T / 64; chunk += F.G) {
;         __syncthreads();
;         if (F.tid < 64) lc[F.tid] = 0;
;         const bf16* XB = (const bf16*)(F.ws + WS_XB);
;         f32x4 g1[4], vlg[4], vlb[4], sc1[4], sh[4];
;         { const float* modp = MOD + ((size_t)l * 8 + ((chunk * 64) >> 11)) * 6144;
;           load_row(modp + 2048, lane, g1); load_row(F.in[12] + (l * 2 + 0) * D, lane, vlg); load_row(F.in[13] + (l * 2 + 0) * D, lane, vlb); load_row(modp + 3 * 1024, lane, sh); load_row(modp + 4 * 1024, lane, sc1);
; #pragma unroll
;           for (int j = 0; j < 4; ++j) { g1[j] = g1[j] + 1.f; sc1[j] = sc1[j] + 1.f; } }
;         f32x4 cx[4], nx[4]; u32x2 cy[4], ny[4];
;         { const int row = chunk * 64 + w * 8; if (l == 0) load_row(F.in[0] + (size_t)row * D, lane, cx); else load_row_bf16(XB + (size_t)row * D, lane, cx);
; #pragma unroll
;           for (int j = 0; j < 4; ++j) cy[j] = *(const u32x2*)((const bf16*)(F.ws + WS_MIX) + (size_t)row * D + 256 * j + 4 * lane); }
;         for (int i = 0; i < 8; ++i) {
;             const int row = chunk * 64 + w * 8 + i, b = row >> 11;
;             const float* modp = MOD + ((size_t)l * 8 + b) * 6144;
;             if (i + 1 < 8) { if (l == 0) load_row(F.in[0] + (size_t)(row + 1) * D, lane, nx); else load_row_bf16(XB + (size_t)(row + 1) * D, lane, nx);
; #pragma unroll
;                 for (int j = 0; j < 4; ++j) ny[j] = *(const u32x2*)((const bf16*)(F.ws + WS_MIX) + (size_t)(row + 1) * D + 256 * j + 4 * lane); }
;             f32x4 x[4], y[4];
; #pragma unroll
;             for (int j = 0; j < 4; ++j) { x[j] = cx[j]; y[j] = bf4(cy[j]); }
.LBB0_2140:
	v_lshl_add_u64 v[146:147], v[118:119], 0, s[26:27]
	global_load_dwordx2 v[152:153], v[146:147], off
	global_load_dwordx2 v[150:151], v[146:147], off offset:512
	global_load_dwordx2 v[148:149], v[146:147], off offset:1024
	s_nop 0
	global_load_dwordx2 v[146:147], v[146:147], off offset:1536
	v_and_b32_e32 v158, 64, v225
	v_add_u32_e32 v163, 64, v158
	v_xor_b32_e32 v135, 32, v225
	v_cmp_lt_i32_e32 vcc, v135, v163
	v_xor_b32_e32 v159, 16, v225
	v_xor_b32_e32 v160, 8, v225
	v_cndmask_b32_e32 v135, v225, v135, vcc
	v_cmp_lt_i32_e32 vcc, v159, v163
	v_xor_b32_e32 v161, 4, v225
	v_xor_b32_e32 v162, 2, v225
	v_cndmask_b32_e32 v159, v225, v159, vcc
	v_cmp_lt_i32_e32 vcc, v160, v163
	v_xor_b32_e32 v164, 1, v225
	s_waitcnt vmcnt(21)
	v_pk_add_f32 v[96:97], v[96:97], 1.0 op_sel_hi:[1,0]
	v_cndmask_b32_e32 v160, v225, v160, vcc
	v_cmp_lt_i32_e32 vcc, v161, v163
	v_pk_add_f32 v[94:95], v[94:95], 1.0 op_sel_hi:[1,0]
	s_waitcnt vmcnt(5)
	v_pk_add_f32 v[112:113], v[112:113], 1.0 op_sel_hi:[1,0]
	v_cndmask_b32_e32 v161, v225, v161, vcc
	v_cmp_lt_i32_e32 vcc, v162, v163
	v_pk_add_f32 v[110:111], v[110:111], 1.0 op_sel_hi:[1,0]
	v_pk_add_f32 v[92:93], v[92:93], 1.0 op_sel_hi:[1,0]
	v_cndmask_b32_e32 v162, v225, v162, vcc
	v_cmp_lt_i32_e32 vcc, v164, v163
	v_pk_add_f32 v[90:91], v[90:91], 1.0 op_sel_hi:[1,0]
	v_pk_add_f32 v[108:109], v[108:109], 1.0 op_sel_hi:[1,0]
	v_cndmask_b32_e32 v163, v225, v164, vcc
	v_pk_add_f32 v[106:107], v[106:107], 1.0 op_sel_hi:[1,0]
	v_pk_add_f32 v[88:89], v[88:89], 1.0 op_sel_hi:[1,0]
	v_pk_add_f32 v[86:87], v[86:87], 1.0 op_sel_hi:[1,0]
	v_pk_add_f32 v[104:105], v[104:105], 1.0 op_sel_hi:[1,0]
	v_pk_add_f32 v[102:103], v[102:103], 1.0 op_sel_hi:[1,0]
	v_pk_add_f32 v[84:85], v[84:85], 1.0 op_sel_hi:[1,0]
	v_pk_add_f32 v[82:83], v[82:83], 1.0 op_sel_hi:[1,0]
	s_waitcnt vmcnt(0)
	v_pk_add_f32 v[100:101], v[100:101], 1.0 op_sel_hi:[1,0]
	v_pk_add_f32 v[98:99], v[98:99], 1.0 op_sel_hi:[1,0]
	s_mov_b32 s6, 0
	v_lshlrev_b32_e32 v135, 2, v135
	v_lshlrev_b32_e32 v159, 2, v159
	v_lshlrev_b32_e32 v160, 2, v160
	v_lshlrev_b32_e32 v161, 2, v161
	v_lshlrev_b32_e32 v162, 2, v162
	v_lshlrev_b32_e32 v163, 2, v163
	s_add_i32 s26, s11, s6
	s_cmp_eq_u32 s6, 7
	s_cbranch_scc1 .LBB0_2147
	s_branch .LBB0_2142
.LBB0_2141:
	s_waitcnt vmcnt(12)
	s_bitcmp1_b32 s28, 0
	s_cbranch_scc0 .Lr1_nocvt
	v_lshlrev_b32_e32 v2, 16, v4
	v_and_b32_e32 v3, 0xffff0000, v4
	v_lshlrev_b32_e32 v4, 16, v5
	v_and_b32_e32 v5, 0xffff0000, v5
	v_lshlrev_b32_e32 v6, 16, v8
	v_and_b32_e32 v7, 0xffff0000, v8
	v_lshlrev_b32_e32 v8, 16, v9
	v_and_b32_e32 v9, 0xffff0000, v9
	v_lshlrev_b32_e32 v10, 16, v12
	v_and_b32_e32 v11, 0xffff0000, v12
	v_lshlrev_b32_e32 v12, 16, v13
	v_and_b32_e32 v13, 0xffff0000, v13
	v_lshlrev_b32_e32 v14, 16, v16
	v_and_b32_e32 v15, 0xffff0000, v16
	v_lshlrev_b32_e32 v16, 16, v17
	v_and_b32_e32 v17, 0xffff0000, v17

; __device__ __forceinline__ void load_row_bf16(const bf16* p, int lane, f32x4 (&v)[4]) {
; #pragma unroll
;     for (int j = 0; j < 4; ++j) { const u32x2 q = *(const u32x2*)(p + 256 * j + 4 * lane);
;         v[j] = (f32x4){__uint_as_float(q.x << 16), __uint_as_float(q.x & 0xffff0000u), __uint_as_float(q.y << 16), __uint_as_float(q.y & 0xffff0000u)}; }
; }
; __device__ __forceinline__ void phase_row1(const Frame& F, int l) {
;     ...
;         for (int i = 0; i < 8; ++i) {
;             const int row = chunk * 64 + w * 8 + i, b = row >> 11;
;             const float* modp = MOD + ((size_t)l * 8 + b) * 6144;
;             if (i + 1 < 8) { if (l == 0) load_row(F.in[0] + (size_t)(row + 1) * D, lane, nx); else load_row_bf16(XB + (size_t)(row + 1) * D, lane, nx);
; #pragma unroll
;                 for (int j = 0; j < 4; ++j) ny[j] = *(const u32x2*)((const bf16*)(F.ws + WS_MIX) + (size_t)(row + 1) * D + 256 * j + 4 * lane); }
.LBB0_2142:
	s_add_i32 s44, s26, 1
	s_ashr_i32 s45, s44, 31
	s_and_b64 vcc, exec, s[28:29]
	s_cbranch_vccz .LBB0_2146
	s_lshl_b64 s[46:47], s[44:45], 11
	v_lshl_add_u64 v[14:15], v[116:117], 0, s[46:47]
	global_load_dwordx2 v[4:5], v[14:15], off
	global_load_dwordx2 v[8:9], v[14:15], off offset:512
	global_load_dwordx2 v[12:13], v[14:15], off offset:1024
	global_load_dwordx2 v[16:17], v[14:15], off offset:1536
	s_cbranch_execnz .LBB0_2145

; __device__ __forceinline__ void ln_stats(const f32x4 (&v)[4], float& mean, float& rstd) {
;     float s = 0.f;
; #pragma unroll
;     for (int j = 0; j < 4; ++j) s += (v[j].x + v[j].y) + (v[j].z + v[j].w);
;     mean = wsum(s) * (1.f / D);
;     float s2 = 0.f;
; #pragma unroll
;     for (int j = 0; j < 4; ++j) { const f32x4 d = v[j] - mean; s2 += (d.x * d.x + d.y * d.y) + (d.z * d.z + d.w * d.w); }
;     rstd = 1.f / sqrtf(wsum(s2) * (1.f / D) + LN_EPS);
; }
; __device__ __forceinline__ void deepnorm_r(f32x4 (&x)[4], const f32x4 (&y)[4], const f32x4 (&g1)[4], const f32x4 (&lg)[4], const f32x4 (&lb)[4]) {
; #pragma unroll
;     for (int j = 0; j < 4; ++j) x[j] = ALPHA * x[j] + g1[j] * y[j];
;     float mean, rstd; ln_stats(x, mean, rstd);
.LBB0_2147:
	v_lshlrev_b32_e32 v164, 16, v152
	v_and_b32_e32 v165, 0xffff0000, v152
	v_lshlrev_b32_e32 v152, 16, v153
	v_and_b32_e32 v153, 0xffff0000, v153
	v_lshlrev_b32_e32 v168, 16, v148
	v_and_b32_e32 v169, 0xffff0000, v148
	v_lshlrev_b32_e32 v148, 16, v149
	v_and_b32_e32 v149, 0xffff0000, v149
	v_lshlrev_b32_e32 v166, 16, v150
	v_and_b32_e32 v167, 0xffff0000, v150
	v_lshlrev_b32_e32 v150, 16, v151
	v_and_b32_e32 v151, 0xffff0000, v151
	v_lshlrev_b32_e32 v170, 16, v146
	v_and_b32_e32 v171, 0xffff0000, v146
	v_lshlrev_b32_e32 v146, 16, v147
	v_and_b32_e32 v147, 0xffff0000, v147
	v_pk_mul_f32 v[164:165], v[94:95], v[164:165]
	v_pk_mul_f32 v[152:153], v[96:97], v[152:153]
	v_pk_mul_f32 v[148:149], v[88:89], v[148:149]
	v_pk_fma_f32 v[80:81], v[80:81], s[16:17], v[152:153] op_sel_hi:[1,0,1]
	v_pk_fma_f32 v[78:79], v[78:79], s[16:17], v[164:165] op_sel_hi:[1,0,1]
	v_pk_mul_f32 v[152:153], v[90:91], v[166:167]
	v_pk_mul_f32 v[150:151], v[92:93], v[150:151]
	v_pk_fma_f32 v[72:73], v[72:73], s[16:17], v[148:149] op_sel_hi:[1,0,1]
	v_pk_mul_f32 v[148:149], v[82:83], v[170:171]
	v_pk_mul_f32 v[146:147], v[84:85], v[146:147]
	v_pk_fma_f32 v[76:77], v[76:77], s[16:17], v[150:151] op_sel_hi:[1,0,1]
	v_pk_fma_f32 v[74:75], v[74:75], s[16:17], v[152:153] op_sel_hi:[1,0,1]
	v_pk_mul_f32 v[150:151], v[86:87], v[168:169]
	v_pk_fma_f32 v[68:69], v[68:69], s[16:17], v[146:147] op_sel_hi:[1,0,1]
	v_pk_fma_f32 v[66:67], v[66:67], s[16:17], v[148:149] op_sel_hi:[1,0,1]
	v_pk_mov_b32 v[146:147], v[78:79], v[80:81] op_sel:[1,0]
	v_mov_b32_e32 v148, v78
	v_mov_b32_e32 v149, v81
	v_pk_fma_f32 v[70:71], v[70:71], s[16:17], v[150:151] op_sel_hi:[1,0,1]
	v_pk_add_f32 v[146:147], v[146:147], v[148:149]
	v_pk_mov_b32 v[148:149], v[74:75], v[76:77] op_sel:[1,0]
	v_mov_b32_e32 v150, v74
	v_mov_b32_e32 v151, v77
	v_pk_add_f32 v[148:149], v[148:149], v[150:151]
	v_add_f32_e32 v146, v146, v147
	v_pk_add_f32 v[148:149], v[148:149], v[148:149] op_sel:[0,1] op_sel_hi:[1,0]
	v_add_f32_e32 v146, 0, v146
	v_add_f32_e32 v150, v70, v71
	v_add_f32_e32 v152, v72, v73
	v_mov_b32_e32 v147, v66
	v_mov_b32_e32 v149, v67
	v_mov_b32_e32 v151, v68
	v_mov_b32_e32 v153, v69
	v_pk_add_f32 v[146:147], v[146:147], v[148:149]
	v_pk_add_f32 v[148:149], v[150:151], v[152:153]
	s_ashr_i32 s27, s26, 31
	v_pk_add_f32 v[146:147], v[146:147], v[148:149]
	s_lshl_b64 s[30:31], s[26:27], 11
	v_add_f32_e32 v146, v146, v147
	ds_bpermute_b32 v147, v135, v146
	s_mov_b32 s7, 0x1e3ce508
	s_waitcnt lgkmcnt(0)
	v_add_f32_e32 v146, v146, v147
	ds_bpermute_b32 v147, v159, v146
	s_waitcnt lgkmcnt(0)
	v_add_f32_e32 v146, v146, v147
	ds_bpermute_b32 v147, v160, v146
	s_waitcnt lgkmcnt(0)
	v_add_f32_e32 v146, v146, v147
	ds_bpermute_b32 v147, v161, v146
	s_waitcnt lgkmcnt(0)
	v_add_f32_e32 v146, v146, v147
	ds_bpermute_b32 v147, v162, v146
	s_waitcnt lgkmcnt(0)
	v_add_f32_e32 v146, v146, v147
	ds_bpermute_b32 v147, v163, v146
	s_waitcnt lgkmcnt(0)
	v_add_f32_e32 v164, v146, v147
	v_fmamk_f32 v79, v164, 0xba800000, v79
	v_fmac_f32_e32 v78, 0xba800000, v164
	v_fmamk_f32 v81, v164, 0xba800000, v81
	v_fmac_f32_e32 v80, 0xba800000, v164
	v_pk_mul_f32 v[146:147], v[80:81], v[80:81]
	v_pk_mul_f32 v[148:149], v[78:79], v[78:79]
	v_fmamk_f32 v75, v164, 0xba800000, v75
	v_pk_mov_b32 v[150:151], v[148:149], v[146:147] op_sel:[1,0]
	v_mov_b32_e32 v149, v147
	v_pk_add_f32 v[146:147], v[150:151], v[148:149]
	v_fmac_f32_e32 v74, 0xba800000, v164
	v_fmamk_f32 v77, v164, 0xba800000, v77
	v_fmac_f32_e32 v76, 0xba800000, v164
	v_pk_add_f32 v[146:147], v[146:147], v[146:147] op_sel_hi:[0,1]
	v_pk_mul_f32 v[148:149], v[76:77], v[76:77]
	v_pk_mul_f32 v[150:151], v[74:75], v[74:75]
	v_fmac_f32_e32 v70, 0xba800000, v164
	v_pk_mov_b32 v[152:153], v[150:151], v[148:149] op_sel:[1,0]
	v_mov_b32_e32 v151, v149
	v_fmamk_f32 v71, v164, 0xba800000, v71
	v_fmac_f32_e32 v72, 0xba800000, v164
	v_mul_f32_e32 v146, v70, v70
	v_pk_add_f32 v[148:149], v[152:153], v[150:151]
	v_fmamk_f32 v73, v164, 0xba800000, v73
	v_pk_fma_f32 v[150:151], v[70:71], v[70:71], v[146:147] op_sel_hi:[1,1,0]
	v_mul_f32_e32 v146, v72, v72
	v_pk_add_f32 v[148:149], v[148:149], v[148:149] op_sel_hi:[0,1]
	v_pk_fma_f32 v[152:153], v[72:73], v[72:73], v[146:147] op_sel_hi:[1,1,0]
	v_fmamk_f32 v69, v164, 0xba800000, v69
	v_fmac_f32_e32 v68, 0xba800000, v164
	v_fmamk_f32 v67, v164, 0xba800000, v67
	v_fmac_f32_e32 v66, 0xba800000, v164
	v_mul_f32_e32 v150, v66, v66
	v_mul_f32_e32 v152, v67, v67
	v_mul_f32_e32 v146, v68, v68
	v_mul_f32_e32 v148, v69, v69
	v_pk_add_f32 v[150:151], v[150:151], v[152:153]
	v_pk_add_f32 v[146:147], v[146:147], v[148:149]
	s_nop 0
	v_pk_add_f32 v[146:147], v[150:151], v[146:147]
	s_nop 0
	v_add_f32_e32 v146, v146, v147
	ds_bpermute_b32 v147, v135, v146
	s_waitcnt lgkmcnt(0)
	v_add_f32_e32 v146, v146, v147
	ds_bpermute_b32 v147, v159, v146
	s_waitcnt lgkmcnt(0)
	v_add_f32_e32 v146, v146, v147
	ds_bpermute_b32 v147, v160, v146
	s_waitcnt lgkmcnt(0)
	v_add_f32_e32 v146, v146, v147
	ds_bpermute_b32 v147, v161, v146
	s_waitcnt lgkmcnt(0)
	v_add_f32_e32 v146, v146, v147
	ds_bpermute_b32 v147, v162, v146
	s_waitcnt lgkmcnt(0)
	v_add_f32_e32 v146, v146, v147
	ds_bpermute_b32 v147, v163, v146
	s_waitcnt lgkmcnt(0)
; __device__ __forceinline__ void ln_stats(const f32x4 (&v)[4], float& mean, float& rstd) {
;     float s = 0.f;
; #pragma unroll
;     for (int j = 0; j < 4; ++j) s += (v[j].x + v[j].y) + (v[j].z + v[j].w);
;     mean = wsum(s) * (1.f / D);
;     float s2 = 0.f;
; #pragma unroll
;     for (int j = 0; j < 4; ++j) { const f32x4 d = v[j] - mean; s2 += (d.x * d.x + d.y * d.y) + (d.z * d.z + d.w * d.w); }
;     rstd = 1.f / sqrtf(wsum(s2) * (1.f / D) + LN_EPS);
; }
; __device__ __forceinline__ void phase_row1(const Frame& F, int l) {
;     ...
;             deepnorm_r(x, y, g1, vlg, vlb);
;             store_row_bf16((bf16*)(F.ws + WS_XB) + (size_t)row * D, lane, x);
;             ada_ln_r(x, sc1, sh);
	v_add_f32_e32 v146, v146, v147
	v_fmamk_f32 v146, v146, 0x3a800000, v226
	v_mul_f32_e32 v147, 0x4f800000, v146
	v_cmp_gt_f32_e32 vcc, s2, v146
	s_nop 1
	v_cndmask_b32_e32 v146, v146, v147, vcc
	v_sqrt_f32_e32 v147, v146
	s_nop 0
	v_add_u32_e32 v148, -1, v147
	v_fma_f32 v149, -v148, v147, v146
	v_cmp_ge_f32_e64 s[44:45], 0, v149
	v_add_u32_e32 v149, 1, v147
	s_nop 0
	v_cndmask_b32_e64 v148, v147, v148, s[44:45]
	v_fma_f32 v147, -v149, v147, v146
	v_cmp_lt_f32_e64 s[44:45], 0, v147
	s_nop 1
	v_cndmask_b32_e64 v147, v148, v149, s[44:45]
	v_mul_f32_e32 v148, 0x37800000, v147
	v_cndmask_b32_e32 v147, v147, v148, vcc
	v_cmp_class_f32_e32 vcc, v146, v227
	s_nop 1
	v_cndmask_b32_e32 v146, v147, v146, vcc
	v_div_scale_f32 v147, s[4:5], v146, v146, 1.0
	v_rcp_f32_e32 v148, v147
	s_nop 0
	v_fma_f32 v149, -v147, v148, 1.0
	v_fmac_f32_e32 v148, v149, v148
	v_div_scale_f32 v149, vcc, 1.0, v146, 1.0
	v_mul_f32_e32 v150, v149, v148
	v_fma_f32 v151, -v147, v150, v149
	v_fmac_f32_e32 v150, v151, v148
	v_fma_f32 v147, -v147, v150, v149
	v_div_fmas_f32 v147, v147, v148, v150
	v_div_fixup_f32 v146, v147, v146, 1.0
	v_pk_mul_f32 v[78:79], v[78:79], v[146:147] op_sel_hi:[1,0]
	v_pk_mul_f32 v[80:81], v[80:81], v[146:147] op_sel_hi:[1,0]
	v_pk_fma_f32 v[78:79], v[18:19], v[78:79], v[34:35]
	v_pk_fma_f32 v[80:81], v[20:21], v[80:81], v[36:37]
	v_pk_mul_f32 v[74:75], v[74:75], v[146:147] op_sel_hi:[1,0]
	v_pk_mul_f32 v[76:77], v[76:77], v[146:147] op_sel_hi:[1,0]
	v_pk_mul_f32 v[70:71], v[70:71], v[146:147] op_sel_hi:[1,0]
	v_pk_mul_f32 v[68:69], v[68:69], v[146:147] op_sel_hi:[1,0]
	v_pk_fma_f32 v[76:77], v[24:25], v[76:77], v[40:41]
	v_pk_fma_f32 v[74:75], v[22:23], v[74:75], v[38:39]
	v_pk_mul_f32 v[72:73], v[72:73], v[146:147] op_sel_hi:[1,0]
	v_pk_fma_f32 v[150:151], v[26:27], v[70:71], v[42:43]
	v_pk_mul_f32 v[66:67], v[66:67], v[146:147] op_sel_hi:[1,0]
	v_pk_fma_f32 v[146:147], v[32:33], v[68:69], v[48:49]
	v_pk_mov_b32 v[68:69], v[78:79], v[80:81] op_sel:[1,0]
	v_mov_b32_e32 v70, v78
	v_mov_b32_e32 v71, v81
	v_pk_fma_f32 v[148:149], v[28:29], v[72:73], v[44:45]
	v_pk_add_f32 v[68:69], v[68:69], v[70:71]
	v_pk_mov_b32 v[70:71], v[74:75], v[76:77] op_sel:[1,0]
	v_mov_b32_e32 v72, v74
	v_mov_b32_e32 v73, v77
	v_pk_add_f32 v[70:71], v[70:71], v[72:73]
	v_pk_fma_f32 v[66:67], v[30:31], v[66:67], v[46:47]
	v_add_f32_e32 v68, v68, v69
	v_pk_add_f32 v[70:71], v[70:71], v[70:71] op_sel_hi:[0,1]
	v_add_f32_e32 v69, 0, v68
	v_add_f32_e32 v73, v150, v151
	v_add_f32_e32 v153, v148, v149
	v_mov_b32_e32 v72, v66
	v_mov_b32_e32 v152, v67
	v_mov_b32_e32 v70, v146
	v_mov_b32_e32 v68, v147
	v_pk_add_f32 v[72:73], v[72:73], v[152:153]
	v_pk_add_f32 v[68:69], v[70:71], v[68:69]
	v_cvt_pk_bf16_f32 v152, v78, v79
	v_cvt_pk_bf16_f32 v153, v80, v81
	v_cvt_pk_bf16_f32 v164, v74, v75
	v_cvt_pk_bf16_f32 v165, v76, v77
	v_cvt_pk_bf16_f32 v166, v150, v151
	s_nop 0
	v_pk_add_f32 v[68:69], v[72:73], v[68:69]
	v_cvt_pk_bf16_f32 v167, v148, v149
	v_cvt_pk_bf16_f32 v168, v66, v67
	v_cvt_pk_bf16_f32 v169, v146, v147
	s_nop 0
	v_add_f32_e32 v68, v68, v69
	ds_bpermute_b32 v69, v135, v68
	s_waitcnt lgkmcnt(0)
	v_add_f32_e32 v68, v68, v69
	ds_bpermute_b32 v69, v159, v68
	s_waitcnt lgkmcnt(0)
	v_add_f32_e32 v68, v68, v69
	ds_bpermute_b32 v69, v160, v68
	s_waitcnt lgkmcnt(0)
	v_add_f32_e32 v68, v68, v69
	ds_bpermute_b32 v69, v161, v68
	s_waitcnt lgkmcnt(0)
	v_add_f32_e32 v68, v68, v69
	ds_bpermute_b32 v69, v162, v68
	s_waitcnt lgkmcnt(0)
	v_add_f32_e32 v68, v68, v69
	ds_bpermute_b32 v69, v163, v68
	s_waitcnt lgkmcnt(0)
	v_add_f32_e32 v172, v68, v69
	v_fmamk_f32 v79, v172, 0xba800000, v79
	v_fmac_f32_e32 v78, 0xba800000, v172
	v_fmamk_f32 v81, v172, 0xba800000, v81
	v_fmac_f32_e32 v80, 0xba800000, v172
	v_pk_mul_f32 v[68:69], v[80:81], v[80:81]
	v_pk_mul_f32 v[70:71], v[78:79], v[78:79]
	v_fmamk_f32 v75, v172, 0xba800000, v75
	v_pk_mov_b32 v[72:73], v[70:71], v[68:69] op_sel:[1,0]
	v_mov_b32_e32 v71, v69
	v_pk_add_f32 v[68:69], v[72:73], v[70:71]
	v_fmac_f32_e32 v74, 0xba800000, v172
	v_fmamk_f32 v77, v172, 0xba800000, v77
	v_fmac_f32_e32 v76, 0xba800000, v172
	v_pk_add_f32 v[68:69], v[68:69], v[68:69] op_sel_hi:[0,1]
	v_pk_mul_f32 v[70:71], v[76:77], v[76:77]
	v_pk_mul_f32 v[72:73], v[74:75], v[74:75]
	v_fmac_f32_e32 v150, 0xba800000, v172
	v_pk_mov_b32 v[170:171], v[72:73], v[70:71] op_sel:[1,0]
	v_mov_b32_e32 v73, v71
	v_fmamk_f32 v151, v172, 0xba800000, v151
	v_fmac_f32_e32 v148, 0xba800000, v172
	v_mul_f32_e32 v68, v150, v150
	v_pk_add_f32 v[70:71], v[170:171], v[72:73]
	v_fmamk_f32 v149, v172, 0xba800000, v149
	v_pk_fma_f32 v[72:73], v[150:151], v[150:151], v[68:69] op_sel_hi:[1,1,0]
	v_mul_f32_e32 v68, v148, v148
	v_pk_add_f32 v[70:71], v[70:71], v[70:71] op_sel_hi:[0,1]
	v_pk_fma_f32 v[170:171], v[148:149], v[148:149], v[68:69] op_sel_hi:[1,1,0]
	v_fmamk_f32 v147, v172, 0xba800000, v147
	v_fmac_f32_e32 v146, 0xba800000, v172
	v_fmamk_f32 v67, v172, 0xba800000, v67
	v_fmac_f32_e32 v66, 0xba800000, v172
	v_mul_f32_e32 v72, v66, v66
	v_mul_f32_e32 v170, v67, v67
	v_mul_f32_e32 v68, v146, v146
	v_mul_f32_e32 v70, v147, v147
	v_pk_add_f32 v[72:73], v[72:73], v[170:171]
	v_pk_add_f32 v[68:69], v[68:69], v[70:71]
	s_nop 0
	v_pk_add_f32 v[68:69], v[72:73], v[68:69]
	s_nop 0
	v_add_f32_e32 v68, v68, v69
	ds_bpermute_b32 v69, v135, v68
	s_waitcnt lgkmcnt(0)
	v_add_f32_e32 v68, v68, v69
	ds_bpermute_b32 v69, v159, v68
	s_waitcnt lgkmcnt(0)
	v_add_f32_e32 v68, v68, v69
	ds_bpermute_b32 v69, v160, v68
	s_waitcnt lgkmcnt(0)
	v_add_f32_e32 v68, v68, v69
	ds_bpermute_b32 v69, v161, v68
	s_waitcnt lgkmcnt(0)
; __device__ __forceinline__ unsigned pk4_fp8(f32x4 v) { int r = 0; r = __builtin_amdgcn_cvt_pk_fp8_f32(v.x, v.y, r, false); r = __builtin_amdgcn_cvt_pk_fp8_f32(v.z, v.w, r, true); return (unsigned)r; }
; __device__ __forceinline__ void ln_stats(const f32x4 (&v)[4], float& mean, float& rstd) {
;     ...
;     for (int j = 0; j < 4; ++j) { const f32x4 d = v[j] - mean; s2 += (d.x * d.x + d.y * d.y) + (d.z * d.z + d.w * d.w); }
;     rstd = 1.f / sqrtf(wsum(s2) * (1.f / D) + LN_EPS);
; __device__ __forceinline__ void phase_row1(const Frame& F, int l) {
;     ...
;             deepnorm_r(x, y, g1, vlg, vlb);
;             store_row_bf16((bf16*)(F.ws + WS_XB) + (size_t)row * D, lane, x);
;             ada_ln_r(x, sc1, sh);
;             store_row(H32 + (size_t)row * D, lane, x);
;             {
;                 float am = 0.f;
; #pragma unroll
;                 for (int j = 0; j < 4; ++j) am = fmaxf(am, fmaxf(fmaxf(fabsf(x[j].x), fabsf(x[j].y)), fmaxf(fabsf(x[j].z), fabsf(x[j].w))));
;                 am = fmaxf(wmaxf(am), 1e-20f);
;                 const float qs = 224.f / am;
;                 unsigned char* hq = (unsigned char*)(F.ws + WS_HQ) + (size_t)row * D;
; #pragma unroll
;                 for (int j = 0; j < 4; ++j) *(unsigned*)(hq + 256 * j + 4 * lane) = pk4_fp8(x[j] * qs);
;                 if (lane == 0) ((float*)(F.ws + WS_HS))[row] = am * (1.f / 224.f);
	v_add_f32_e32 v68, v68, v69
	ds_bpermute_b32 v69, v162, v68
	s_waitcnt lgkmcnt(0)
	v_add_f32_e32 v68, v68, v69
	ds_bpermute_b32 v69, v163, v68
	s_waitcnt lgkmcnt(0)
	v_add_f32_e32 v68, v68, v69
	v_fmamk_f32 v68, v68, 0x3a800000, v226
	v_mul_f32_e32 v69, 0x4f800000, v68
	v_cmp_gt_f32_e32 vcc, s2, v68
	s_nop 1
	v_cndmask_b32_e32 v68, v68, v69, vcc
	v_sqrt_f32_e32 v69, v68
	s_nop 0
	v_add_u32_e32 v70, -1, v69
	v_fma_f32 v71, -v70, v69, v68
	v_cmp_ge_f32_e64 s[44:45], 0, v71
	v_add_u32_e32 v71, 1, v69
	s_nop 0
	v_cndmask_b32_e64 v70, v69, v70, s[44:45]
	v_fma_f32 v69, -v71, v69, v68
	v_cmp_lt_f32_e64 s[44:45], 0, v69
	s_nop 1
	v_cndmask_b32_e64 v69, v70, v71, s[44:45]
	v_mul_f32_e32 v70, 0x37800000, v69
	v_cndmask_b32_e32 v69, v69, v70, vcc
	v_cmp_class_f32_e32 vcc, v68, v227
	s_nop 1
	v_cndmask_b32_e32 v68, v69, v68, vcc
	v_div_scale_f32 v69, s[4:5], v68, v68, 1.0
	v_rcp_f32_e32 v70, v69
	s_lshl_b64 s[4:5], s[26:27], 10
	v_fma_f32 v71, -v69, v70, 1.0
	v_fmac_f32_e32 v70, v71, v70
	v_div_scale_f32 v71, vcc, 1.0, v68, 1.0
	v_mul_f32_e32 v72, v71, v70
	v_fma_f32 v73, -v69, v72, v71
	v_fmac_f32_e32 v72, v73, v70
	v_fma_f32 v69, -v69, v72, v71
	v_div_fmas_f32 v69, v69, v70, v72
	v_div_fixup_f32 v170, v69, v68, 1.0
	v_pk_mul_f32 v[70:71], v[80:81], v[170:171] op_sel_hi:[1,0]
	v_pk_mul_f32 v[72:73], v[74:75], v[170:171] op_sel_hi:[1,0]
	v_pk_mul_f32 v[74:75], v[76:77], v[170:171] op_sel_hi:[1,0]
	v_pk_mul_f32 v[68:69], v[78:79], v[170:171] op_sel_hi:[1,0]
	v_pk_fma_f32 v[70:71], v[112:113], v[70:71], v[60:61]
	v_pk_fma_f32 v[74:75], v[108:109], v[74:75], v[52:53]
	v_pk_mul_f32 v[66:67], v[66:67], v[170:171] op_sel_hi:[1,0]
	v_pk_fma_f32 v[68:69], v[110:111], v[68:69], v[58:59]
	v_pk_fma_f32 v[72:73], v[106:107], v[72:73], v[50:51]
	v_pk_mul_f32 v[78:79], v[148:149], v[170:171] op_sel_hi:[1,0]
	v_pk_mul_f32 v[80:81], v[146:147], v[170:171] op_sel_hi:[1,0]
	v_pk_fma_f32 v[146:147], v[98:99], v[66:67], v[62:63]
	v_max_f32_e64 v66, |v70|, |v71|
	v_max_f32_e64 v67, |v74|, |v75|
	v_pk_mul_f32 v[76:77], v[150:151], v[170:171] op_sel_hi:[1,0]
	v_pk_fma_f32 v[78:79], v[104:105], v[78:79], v[56:57]
	v_pk_fma_f32 v[148:149], v[100:101], v[80:81], v[64:65]
	v_max3_f32 v66, |v68|, |v69|, v66
	v_max3_f32 v67, |v72|, |v73|, v67
	v_pk_fma_f32 v[76:77], v[102:103], v[76:77], v[54:55]
	v_max3_f32 v66, v66, 0, v67
	v_max_f32_e64 v67, |v78|, |v79|
	v_max_f32_e64 v80, |v148|, |v149|
	v_max3_f32 v67, |v76|, |v77|, v67
	v_max3_f32 v80, |v146|, |v147|, v80
	v_max3_f32 v66, v66, v67, v80
	ds_bpermute_b32 v67, v135, v66
	s_waitcnt lgkmcnt(0)
	v_max_f32_e32 v67, v67, v67
	v_max_f32_e32 v66, v66, v67
	ds_bpermute_b32 v67, v159, v66
	s_waitcnt lgkmcnt(0)
	v_max_f32_e32 v67, v67, v67
	v_max_f32_e32 v66, v66, v67
	ds_bpermute_b32 v67, v160, v66
	s_waitcnt lgkmcnt(0)
	v_max_f32_e32 v67, v67, v67
	v_max_f32_e32 v66, v66, v67
	ds_bpermute_b32 v67, v161, v66
	s_waitcnt lgkmcnt(0)
	v_max_f32_e32 v67, v67, v67
	v_max_f32_e32 v80, v66, v67
	ds_bpermute_b32 v81, v162, v80
	v_lshl_add_u64 v[66:67], v[116:117], 0, s[30:31]
	global_store_dwordx2 v[66:67], v[152:153], off
	global_store_dwordx2 v[66:67], v[164:165], off offset:512
	global_store_dwordx2 v[66:67], v[166:167], off offset:1024
	global_store_dwordx2 v[66:67], v[168:169], off offset:1536
	s_lshl_b64 s[30:31], s[26:27], 12
	s_waitcnt lgkmcnt(0)
	v_max_f32_e32 v81, v81, v81
	v_max_f32_e32 v150, v80, v81
	ds_bpermute_b32 v151, v163, v150
	v_lshl_add_u64 v[80:81], v[114:115], 0, s[30:31]
	global_store_dwordx4 v[80:81], v[68:71], off
	global_store_dwordx4 v[80:81], v[72:75], off offset:1024
	global_store_dwordx4 v[80:81], v[76:79], off offset:2048
	global_store_dwordx4 v[80:81], v[146:149], off offset:3072
	s_waitcnt lgkmcnt(0)
	v_max3_f32 v66, v150, v151, s7
	v_div_scale_f32 v67, s[30:31], v66, v66, s20
	v_rcp_f32_e32 v150, v67
	s_nop 0
	v_fma_f32 v80, -v67, v150, 1.0
	v_fmac_f32_e32 v150, v80, v150
	v_div_scale_f32 v80, vcc, s20, v66, s20
	v_mul_f32_e32 v81, v80, v150
	v_fma_f32 v151, -v67, v81, v80
	v_fmac_f32_e32 v81, v151, v150
	v_fma_f32 v67, -v67, v81, v80
	v_div_fmas_f32 v67, v67, v150, v81
	v_div_fixup_f32 v80, v67, v66, s20
	v_pk_mul_f32 v[68:69], v[68:69], v[80:81] op_sel_hi:[1,0]
	v_mov_b32_e32 v67, 0
	v_cvt_pk_fp8_f32 v67, v68, v69
	v_pk_mul_f32 v[68:69], v[72:73], v[80:81] op_sel_hi:[1,0]
	v_mov_b32_e32 v72, 0
	v_cvt_pk_fp8_f32 v72, v68, v69
	v_pk_mul_f32 v[68:69], v[70:71], v[80:81] op_sel_hi:[1,0]
	v_mov_b32_e32 v70, 0
	v_cvt_pk_fp8_f32 v67, v68, v69 op_sel:[0,0,1]
	v_pk_mul_f32 v[68:69], v[74:75], v[80:81] op_sel_hi:[1,0]
	v_mov_b32_e32 v71, 0
	v_cvt_pk_fp8_f32 v72, v68, v69 op_sel:[0,0,1]
	v_pk_mul_f32 v[68:69], v[76:77], v[80:81] op_sel_hi:[1,0]
	v_lshl_add_u64 v[150:151], v[120:121], 0, s[4:5]
	v_cvt_pk_fp8_f32 v70, v68, v69
	v_pk_mul_f32 v[68:69], v[146:147], v[80:81] op_sel_hi:[1,0]
	s_nop 0
	v_cvt_pk_fp8_f32 v71, v68, v69
	v_pk_mul_f32 v[68:69], v[78:79], v[80:81] op_sel_hi:[1,0]
	s_nop 0
	v_cvt_pk_fp8_f32 v70, v68, v69 op_sel:[0,0,1]
	v_pk_mul_f32 v[68:69], v[148:149], v[80:81] op_sel_hi:[1,0]
	s_nop 0
	v_cvt_pk_fp8_f32 v71, v68, v69 op_sel:[0,0,1]
	global_store_dword v[150:151], v67, off
	global_store_dword v[150:151], v72, off offset:256
	global_store_dword v[150:151], v70, off offset:512
	global_store_dword v[150:151], v71, off offset:768
	s_and_saveexec_b64 s[4:5], s[0:1]
	s_cbranch_execz .LBB0_2149
	s_lshl_b64 s[26:27], s[26:27], 2
	s_add_u32 s26, s54, s26
	v_mul_f32_e32 v66, 0x3b924925, v66
	s_addc_u32 s27, s55, s27
	global_store_dword v199, v66, s[26:27]
